# k18
# baseline (speedup 1.0000x reference)
; __device__ __forceinline__ unsigned cvtpk(float lo, float hi) { f32x2 v = {lo, hi}; bf16x2_t b = __builtin_convertvector(v, bf16x2_t); return __builtin_bit_cast(unsigned, b); }
; template <int X> __device__ __forceinline__ float xorl(float v) { return __int_as_float(__builtin_amdgcn_ds_swizzle(__float_as_int(v), (X << 10) | 0x1f)); }
; __device__ __forceinline__ float sum32(float v) { auto rr = __builtin_amdgcn_permlane32_swap(__float_as_uint(v), __float_as_uint(v), false, false); return __uint_as_float(rr[0]) + __uint_as_float(rr[1]); }
;     __device__ __forceinline__ void operator()(const f32x4 (&acc)[2][2][4][2], const Unit& u, int ui, int wr, int wc, int fr, int fq) const {
;     ...
;         for (int ai = 0; ai < 2; ++ai) {
;             u32x4 raw[4][2];
; #pragma unroll
;             for (int m = 0; m < 4; ++m)
; #pragma unroll
;                 for (int bj = 0; bj < 2; ++bj) raw[m][bj] = *(const u32x4*)(xb + (size_t)(u.pm * 256 + ai * HALF + wr * 64 + m * 16 + fr) * D + col0 + bj * HALF);
; #pragma unroll
;             for (int m = 0; m < 4; ++m) { const int row = u.pm * 256 + ai * HALF + wr * 64 + m * 16 + fr; bf16_t* rp = xb + (size_t)row * D + col0; float ss = 0.f;
; #pragma unroll
;                 for (int bj = 0; bj < 2; ++bj) { f32x4 b0, b1; const u32x4 rw = raw[m][bj];
;                     b0[0] = __uint_as_float(rw.x << 16); b0[1] = __uint_as_float(rw.x & 0xffff0000u); b0[2] = __uint_as_float(rw.y << 16); b0[3] = __uint_as_float(rw.y & 0xffff0000u);
;                     b1[0] = __uint_as_float(rw.z << 16); b1[1] = __uint_as_float(rw.z & 0xffff0000u); b1[2] = __uint_as_float(rw.w << 16); b1[3] = __uint_as_float(rw.w & 0xffff0000u);
;                     const f32x4 o0 = b0 + acc[ai][bj][m][0] * cs[bj][0], o1 = b1 + acc[ai][bj][m][1] * cs[bj][1];
;                     ss += ((o0[0] * o0[0] + o0[1] * o0[1]) + (o0[2] * o0[2] + o0[3] * o0[3])) + ((o1[0] * o1[0] + o1[1] * o1[1]) + (o1[2] * o1[2] + o1[3] * o1[3]));
;                     u32x4 w; w.x = cvtpk(o0[0], o0[1]); w.y = cvtpk(o0[2], o0[3]); w.z = cvtpk(o1[0], o1[1]); w.w = cvtpk(o1[2], o1[3]); *(u32x4*)(rp + bj * HALF) = w; }
;                 ss += xorl<16>(ss); ss = sum32(ss);
;                 if (fq == 0) ssq[(size_t)row * 16 + u.pn * 4 + wc] = ss; }
.LBB0_1240:
	v_mbcnt_lo_u32_b32 v130, -1, 0
	v_mbcnt_hi_u32_b32 v130, -1, v130
	s_lshl_b32 s12, s43, 8
	v_ashrrev_i32_e32 v131, 1, v130
	v_and_b32_e32 v131, -8, v131
	s_or_b32 s12, s12, s50
	v_add_u32_e32 v164, s12, v131
	v_and_or_b32 v131, v130, 15, s49
	v_ashrrev_i32_e32 v165, 31, v164
	v_lshl_add_u32 v168, s16, 8, v131
	v_lshlrev_b64 v[192:193], 1, v[164:165]
	v_ashrrev_i32_e32 v169, 31, v168
	v_lshl_add_u64 v[166:167], s[8:9], 0, v[192:193]
	v_lshlrev_b64 v[194:195], 11, v[168:169]
	v_cmp_gt_u32_e32 vcc, 16, v130
	v_lshl_add_u64 v[130:131], v[166:167], 0, v[194:195]
	global_load_dwordx4 v[184:187], v[130:131], off
	global_load_dwordx4 v[188:191], v[130:131], off offset:256
	v_or_b32_e32 v176, 16, v168
	v_ashrrev_i32_e32 v177, 31, v176
	v_or_b32_e32 v172, 32, v168
	v_lshlrev_b64 v[180:181], 11, v[176:177]
	v_ashrrev_i32_e32 v173, 31, v172
	v_or_b32_e32 v170, 48, v168
	v_lshl_add_u64 v[130:131], v[166:167], 0, v[180:181]
	v_lshlrev_b64 v[178:179], 11, v[172:173]
	v_ashrrev_i32_e32 v171, 31, v170
	global_load_dwordx4 v[150:153], v[130:131], off
	global_load_dwordx4 v[146:149], v[130:131], off offset:256
	v_lshl_add_u64 v[130:131], v[166:167], 0, v[178:179]
	v_lshlrev_b64 v[174:175], 11, v[170:171]
	global_load_dwordx4 v[142:145], v[130:131], off
	global_load_dwordx4 v[138:141], v[130:131], off offset:256
	v_lshl_add_u64 v[130:131], v[166:167], 0, v[174:175]
	global_load_dwordx4 v[134:137], v[130:131], off
	s_nop 0
	global_load_dwordx4 v[130:133], v[130:131], off offset:256
	v_add_u32_e32 v206, 0x80, v168
	v_ashrrev_i32_e32 v207, 31, v206
	v_lshlrev_b64 v[206:207], 11, v[206:207]
	v_lshl_add_u64 v[206:207], v[166:167], 0, v[206:207]
	global_load_dwordx4 v[218:221], v[206:207], off
	global_load_dwordx4 v[222:225], v[206:207], off offset:256
	v_add_u32_e32 v206, 0x90, v168
	v_ashrrev_i32_e32 v207, 31, v206
	v_lshlrev_b64 v[206:207], 11, v[206:207]
	v_lshl_add_u64 v[206:207], v[166:167], 0, v[206:207]
	global_load_dwordx4 v[226:229], v[206:207], off
	global_load_dwordx4 v[230:233], v[206:207], off offset:256
	v_add_u32_e32 v206, 0xa0, v168
	v_ashrrev_i32_e32 v207, 31, v206
	v_lshlrev_b64 v[206:207], 11, v[206:207]
	v_lshl_add_u64 v[206:207], v[166:167], 0, v[206:207]
	global_load_dwordx4 v[234:237], v[206:207], off
	global_load_dwordx4 v[238:241], v[206:207], off offset:256
	v_add_u32_e32 v206, 0xb0, v168
	v_ashrrev_i32_e32 v207, 31, v206
	v_lshlrev_b64 v[206:207], 11, v[206:207]
	v_lshl_add_u64 v[206:207], v[166:167], 0, v[206:207]
	global_load_dwordx4 v[242:245], v[206:207], off
	global_load_dwordx4 v[246:249], v[206:207], off offset:256
	v_lshl_add_u64 v[194:195], s[8:9], 0, v[194:195]
	v_lshl_add_u64 v[192:193], v[194:195], 0, v[192:193]
	s_waitcnt vmcnt(8)
	v_lshlrev_b32_e32 v194, 16, v184
	v_and_b32_e32 v195, 0xffff0000, v184
	v_lshlrev_b32_e32 v184, 16, v185
	v_and_b32_e32 v185, 0xffff0000, v185
	v_lshlrev_b32_e32 v196, 16, v186
	v_and_b32_e32 v197, 0xffff0000, v186
	v_lshlrev_b32_e32 v186, 16, v187
	v_and_b32_e32 v187, 0xffff0000, v187
	v_pk_add_f32 v[128:129], v[128:129], v[184:185]
	v_pk_add_f32 v[126:127], v[126:127], v[194:195]
	v_pk_add_f32 v[184:185], v[124:125], v[186:187]
	v_pk_add_f32 v[124:125], v[122:123], v[196:197]
	v_mul_f32_e32 v122, v127, v127
	v_mul_f32_e32 v123, v129, v129
	v_fmac_f32_e32 v122, v126, v126
	v_fmac_f32_e32 v123, v128, v128
	v_add_f32_e32 v122, v122, v123
	v_mul_f32_e32 v123, v125, v125
	v_mul_f32_e32 v186, v185, v185
	v_fmac_f32_e32 v123, v124, v124
	v_fmac_f32_e32 v186, v184, v184
	v_add_f32_e32 v123, v123, v186
	v_add_f32_e32 v186, v122, v123
	v_cvt_pk_bf16_f32 v122, v126, v127
	v_cvt_pk_bf16_f32 v123, v128, v129
	v_cvt_pk_bf16_f32 v124, v124, v125
	v_cvt_pk_bf16_f32 v125, v184, v185
	global_store_dwordx4 v[192:193], v[122:125], off
	v_lshlrev_b32_e32 v126, 16, v190
	v_and_b32_e32 v127, 0xffff0000, v190
	v_lshlrev_b32_e32 v122, 16, v188
	v_and_b32_e32 v123, 0xffff0000, v188
	v_lshlrev_b32_e32 v124, 16, v189
	v_and_b32_e32 v125, 0xffff0000, v189
	v_lshlrev_b32_e32 v128, 16, v191
	v_and_b32_e32 v129, 0xffff0000, v191
	v_pk_add_f32 v[120:121], v[120:121], v[124:125]
	v_pk_add_f32 v[118:119], v[118:119], v[122:123]
	v_pk_add_f32 v[122:123], v[116:117], v[128:129]
	v_pk_add_f32 v[116:117], v[114:115], v[126:127]
	v_mul_f32_e32 v114, v119, v119
	v_mul_f32_e32 v115, v121, v121
	v_fmac_f32_e32 v114, v118, v118
	v_fmac_f32_e32 v115, v120, v120
	v_add_f32_e32 v114, v114, v115
	v_mul_f32_e32 v115, v117, v117
	v_mul_f32_e32 v124, v123, v123
	v_fmac_f32_e32 v115, v116, v116
	v_fmac_f32_e32 v124, v122, v122
	v_add_f32_e32 v115, v115, v124
	v_add_f32_e32 v114, v114, v115
	v_add_f32_e32 v124, v186, v114
	v_cvt_pk_bf16_f32 v114, v118, v119
	v_cvt_pk_bf16_f32 v115, v120, v121
	v_cvt_pk_bf16_f32 v116, v116, v117
	v_cvt_pk_bf16_f32 v117, v122, v123
	global_store_dwordx4 v[192:193], v[114:117], off offset:256
	ds_swizzle_b32 v114, v124 offset:swizzle(SWAP,16)
	s_waitcnt lgkmcnt(0)
	v_add_f32_e32 v114, v124, v114
	v_mov_b32_e32 v115, v114
	s_nop 1
	v_permlane32_swap_b32_e32 v114, v115
	s_and_saveexec_b64 s[28:29], vcc
	s_cbranch_execz .LBB0_1242
	v_add_f32_e32 v116, v114, v115
	s_lshl_b32 s30, s43, 2
	v_lshlrev_b64 v[114:115], 6, v[168:169]
	s_ashr_i32 s31, s30, 31
	v_lshl_add_u64 v[114:115], s[10:11], 0, v[114:115]
	v_lshl_add_u64 v[114:115], s[30:31], 2, v[114:115]
	s_lshl_b32 s16, s48, 2
	v_lshl_add_u64 v[114:115], v[114:115], 0, s[16:17]
	global_store_dword v[114:115], v116, off

; __device__ __forceinline__ unsigned cvtpk(float lo, float hi) { f32x2 v = {lo, hi}; bf16x2_t b = __builtin_convertvector(v, bf16x2_t); return __builtin_bit_cast(unsigned, b); }
; template <int X> __device__ __forceinline__ float xorl(float v) { return __int_as_float(__builtin_amdgcn_ds_swizzle(__float_as_int(v), (X << 10) | 0x1f)); }
; __device__ __forceinline__ float sum32(float v) { auto rr = __builtin_amdgcn_permlane32_swap(__float_as_uint(v), __float_as_uint(v), false, false); return __uint_as_float(rr[0]) + __uint_as_float(rr[1]); }
;     __device__ __forceinline__ void operator()(const f32x4 (&acc)[2][2][4][2], const Unit& u, int ui, int wr, int wc, int fr, int fq) const {
;     ...
;                 for (int bj = 0; bj < 2; ++bj) raw[m][bj] = *(const u32x4*)(xb + (size_t)(u.pm * 256 + ai * HALF + wr * 64 + m * 16 + fr) * D + col0 + bj * HALF);
; #pragma unroll
;             for (int m = 0; m < 4; ++m) { const int row = u.pm * 256 + ai * HALF + wr * 64 + m * 16 + fr; bf16_t* rp = xb + (size_t)row * D + col0; float ss = 0.f;
; #pragma unroll
;                 for (int bj = 0; bj < 2; ++bj) { f32x4 b0, b1; const u32x4 rw = raw[m][bj];
;                     b0[0] = __uint_as_float(rw.x << 16); b0[1] = __uint_as_float(rw.x & 0xffff0000u); b0[2] = __uint_as_float(rw.y << 16); b0[3] = __uint_as_float(rw.y & 0xffff0000u);
;                     b1[0] = __uint_as_float(rw.z << 16); b1[1] = __uint_as_float(rw.z & 0xffff0000u); b1[2] = __uint_as_float(rw.w << 16); b1[3] = __uint_as_float(rw.w & 0xffff0000u);
;                     const f32x4 o0 = b0 + acc[ai][bj][m][0] * cs[bj][0], o1 = b1 + acc[ai][bj][m][1] * cs[bj][1];
;                     ss += ((o0[0] * o0[0] + o0[1] * o0[1]) + (o0[2] * o0[2] + o0[3] * o0[3])) + ((o1[0] * o1[0] + o1[1] * o1[1]) + (o1[2] * o1[2] + o1[3] * o1[3]));
;                     u32x4 w; w.x = cvtpk(o0[0], o0[1]); w.y = cvtpk(o0[2], o0[3]); w.z = cvtpk(o1[0], o1[1]); w.w = cvtpk(o1[2], o1[3]); *(u32x4*)(rp + bj * HALF) = w; }
;                 ss += xorl<16>(ss); ss = sum32(ss);
;                 if (fq == 0) ssq[(size_t)row * 16 + u.pn * 4 + wc] = ss; }
.LBB0_1248:
	s_or_b64 exec, exec, s[28:29]
	v_add_u32_e32 v96, 0x80, v168
	v_ashrrev_i32_e32 v97, 31, v96
	v_lshlrev_b64 v[108:109], 11, v[96:97]
	v_lshl_add_u64 v[66:67], v[166:167], 0, v[108:109]
	s_waitcnt vmcnt(8)
	v_mov_b64_e32 v[100:101], v[218:219]
	v_mov_b64_e32 v[102:103], v[220:221]
	v_mov_b64_e32 v[104:105], v[222:223]
	v_mov_b64_e32 v[106:107], v[224:225]
	v_add_u32_e32 v94, 0x90, v168
	v_ashrrev_i32_e32 v95, 31, v94
	v_lshlrev_b64 v[98:99], 11, v[94:95]
	v_add_u32_e32 v92, 0xa0, v168
	v_lshl_add_u64 v[66:67], v[166:167], 0, v[98:99]
	v_ashrrev_i32_e32 v93, 31, v92
	v_mov_b64_e32 v[86:87], v[226:227]
	v_mov_b64_e32 v[88:89], v[228:229]
	v_mov_b64_e32 v[82:83], v[230:231]
	v_mov_b64_e32 v[84:85], v[232:233]
	v_lshlrev_b64 v[66:67], 11, v[92:93]
	v_add_u32_e32 v90, 0xb0, v168
	v_lshl_add_u64 v[66:67], v[166:167], 0, v[66:67]
	v_ashrrev_i32_e32 v91, 31, v90
	v_mov_b64_e32 v[78:79], v[234:235]
	v_mov_b64_e32 v[80:81], v[236:237]
	v_mov_b64_e32 v[74:75], v[238:239]
	v_mov_b64_e32 v[76:77], v[240:241]
	v_lshlrev_b64 v[66:67], 11, v[90:91]
	v_lshl_add_u64 v[66:67], v[166:167], 0, v[66:67]
	v_mov_b64_e32 v[70:71], v[242:243]
	v_mov_b64_e32 v[72:73], v[244:245]
	s_nop 0
	v_mov_b64_e32 v[66:67], v[246:247]
	v_mov_b64_e32 v[68:69], v[248:249]
	v_lshl_add_u64 v[108:109], s[8:9], 0, v[108:109]
	v_lshl_add_u64 v[108:109], v[164:165], 1, v[108:109]
	v_lshlrev_b32_e32 v110, 16, v100
	v_and_b32_e32 v111, 0xffff0000, v100
	v_lshlrev_b32_e32 v100, 16, v101
	v_and_b32_e32 v101, 0xffff0000, v101
	v_lshlrev_b32_e32 v112, 16, v102
	v_and_b32_e32 v113, 0xffff0000, v102
	v_lshlrev_b32_e32 v102, 16, v103
	v_and_b32_e32 v103, 0xffff0000, v103
	v_pk_add_f32 v[64:65], v[64:65], v[100:101]
	v_pk_add_f32 v[62:63], v[62:63], v[110:111]
	v_pk_add_f32 v[100:101], v[60:61], v[102:103]
	v_pk_add_f32 v[60:61], v[58:59], v[112:113]
	v_mul_f32_e32 v58, v63, v63
	v_mul_f32_e32 v59, v65, v65
	v_fmac_f32_e32 v58, v62, v62
	v_fmac_f32_e32 v59, v64, v64
	v_add_f32_e32 v58, v58, v59
	v_mul_f32_e32 v59, v61, v61
	v_mul_f32_e32 v102, v101, v101
	v_fmac_f32_e32 v59, v60, v60
	v_fmac_f32_e32 v102, v100, v100
	v_add_f32_e32 v59, v59, v102
	v_add_f32_e32 v102, v58, v59
	v_cvt_pk_bf16_f32 v58, v62, v63
	v_cvt_pk_bf16_f32 v59, v64, v65
	v_cvt_pk_bf16_f32 v60, v60, v61
	v_cvt_pk_bf16_f32 v61, v100, v101
	global_store_dwordx4 v[108:109], v[58:61], off
	v_lshlrev_b32_e32 v62, 16, v106
	v_and_b32_e32 v63, 0xffff0000, v106
	v_lshlrev_b32_e32 v58, 16, v104
	v_and_b32_e32 v59, 0xffff0000, v104
	v_lshlrev_b32_e32 v60, 16, v105
	v_and_b32_e32 v61, 0xffff0000, v105
	v_lshlrev_b32_e32 v64, 16, v107
	v_and_b32_e32 v65, 0xffff0000, v107
	v_pk_add_f32 v[56:57], v[56:57], v[60:61]
	v_pk_add_f32 v[54:55], v[54:55], v[58:59]
	v_pk_add_f32 v[58:59], v[52:53], v[64:65]
	v_pk_add_f32 v[52:53], v[50:51], v[62:63]
	v_mul_f32_e32 v50, v55, v55
	v_mul_f32_e32 v51, v57, v57
	v_fmac_f32_e32 v50, v54, v54
	v_fmac_f32_e32 v51, v56, v56
	v_add_f32_e32 v50, v50, v51
	v_mul_f32_e32 v51, v53, v53
	v_mul_f32_e32 v60, v59, v59
	v_fmac_f32_e32 v51, v52, v52
	v_fmac_f32_e32 v60, v58, v58
	v_add_f32_e32 v51, v51, v60
	v_add_f32_e32 v50, v50, v51
	v_add_f32_e32 v60, v102, v50
	v_cvt_pk_bf16_f32 v50, v54, v55
	v_cvt_pk_bf16_f32 v51, v56, v57
	v_cvt_pk_bf16_f32 v52, v52, v53
	v_cvt_pk_bf16_f32 v53, v58, v59
	global_store_dwordx4 v[108:109], v[50:53], off offset:256
	ds_swizzle_b32 v50, v60 offset:swizzle(SWAP,16)
	s_waitcnt lgkmcnt(0)
	v_add_f32_e32 v50, v60, v50
	v_mov_b32_e32 v51, v50
	s_nop 1
	v_permlane32_swap_b32_e32 v50, v51
	s_and_saveexec_b64 s[28:29], vcc
	s_cbranch_execz .LBB0_1250
	v_add_f32_e32 v52, v50, v51
	s_lshl_b32 s30, s43, 2
	v_lshlrev_b64 v[50:51], 6, v[96:97]
	s_ashr_i32 s31, s30, 31
	v_lshl_add_u64 v[50:51], s[10:11], 0, v[50:51]
	v_lshl_add_u64 v[50:51], s[30:31], 2, v[50:51]
	s_lshl_b32 s16, s48, 2
	v_lshl_add_u64 v[50:51], v[50:51], 0, s[16:17]
	global_store_dword v[50:51], v52, off
.LBB0_1250:
	s_or_b64 exec, exec, s[28:29]
	v_lshlrev_b32_e32 v52, 16, v86
	v_and_b32_e32 v53, 0xffff0000, v86
	v_lshlrev_b32_e32 v54, 16, v87
	v_and_b32_e32 v55, 0xffff0000, v87
	v_lshlrev_b32_e32 v56, 16, v88
	v_and_b32_e32 v57, 0xffff0000, v88
	v_lshlrev_b32_e32 v58, 16, v89
	v_and_b32_e32 v59, 0xffff0000, v89
	v_pk_add_f32 v[48:49], v[48:49], v[54:55]
	v_pk_add_f32 v[46:47], v[46:47], v[52:53]
	v_pk_add_f32 v[52:53], v[44:45], v[58:59]
	v_pk_add_f32 v[44:45], v[42:43], v[56:57]
	v_mul_f32_e32 v42, v47, v47
	v_mul_f32_e32 v43, v49, v49
	v_fmac_f32_e32 v42, v46, v46
	v_fmac_f32_e32 v43, v48, v48
	v_add_f32_e32 v42, v42, v43
	v_mul_f32_e32 v43, v45, v45
	v_mul_f32_e32 v54, v53, v53
	v_fmac_f32_e32 v43, v44, v44
	v_fmac_f32_e32 v54, v52, v52
	v_lshl_add_u64 v[50:51], s[8:9], 0, v[98:99]
	v_add_f32_e32 v43, v43, v54
	v_lshl_add_u64 v[50:51], v[164:165], 1, v[50:51]
	v_add_f32_e32 v54, v42, v43
	v_cvt_pk_bf16_f32 v42, v46, v47
	v_cvt_pk_bf16_f32 v43, v48, v49
	v_cvt_pk_bf16_f32 v44, v44, v45
	v_cvt_pk_bf16_f32 v45, v52, v53
	global_store_dwordx4 v[50:51], v[42:45], off
	v_lshlrev_b32_e32 v46, 16, v84
	v_and_b32_e32 v47, 0xffff0000, v84
	v_lshlrev_b32_e32 v42, 16, v82
	v_and_b32_e32 v43, 0xffff0000, v82
	v_lshlrev_b32_e32 v44, 16, v83
	v_and_b32_e32 v45, 0xffff0000, v83
	v_lshlrev_b32_e32 v48, 16, v85
	v_and_b32_e32 v49, 0xffff0000, v85
	v_pk_add_f32 v[40:41], v[40:41], v[44:45]
	v_pk_add_f32 v[38:39], v[38:39], v[42:43]
	v_pk_add_f32 v[42:43], v[36:37], v[48:49]
	v_pk_add_f32 v[36:37], v[34:35], v[46:47]
	v_mul_f32_e32 v34, v39, v39
	v_mul_f32_e32 v35, v41, v41
	v_fmac_f32_e32 v34, v38, v38
	v_fmac_f32_e32 v35, v40, v40
	v_add_f32_e32 v34, v34, v35
	v_mul_f32_e32 v35, v37, v37
	v_mul_f32_e32 v44, v43, v43
	v_fmac_f32_e32 v35, v36, v36
	v_fmac_f32_e32 v44, v42, v42
	v_add_f32_e32 v35, v35, v44
	v_add_f32_e32 v34, v34, v35
	v_add_f32_e32 v44, v54, v34
	v_cvt_pk_bf16_f32 v34, v38, v39
	ds_swizzle_b32 v38, v44 offset:swizzle(SWAP,16)
	v_cvt_pk_bf16_f32 v35, v40, v41
	v_cvt_pk_bf16_f32 v36, v36, v37
	v_cvt_pk_bf16_f32 v37, v42, v43
	global_store_dwordx4 v[50:51], v[34:37], off offset:256
	s_waitcnt lgkmcnt(0)
	s_nop 0
	v_add_f32_e32 v34, v44, v38
	v_mov_b32_e32 v35, v34
	s_nop 1
	v_permlane32_swap_b32_e32 v34, v35
	s_and_saveexec_b64 s[28:29], vcc
	s_cbranch_execz .LBB0_1252
	v_add_f32_e32 v36, v34, v35
	s_lshl_b32 s30, s43, 2
	v_lshlrev_b64 v[34:35], 6, v[94:95]
	s_ashr_i32 s31, s30, 31
	v_lshl_add_u64 v[34:35], s[10:11], 0, v[34:35]
	v_lshl_add_u64 v[34:35], s[30:31], 2, v[34:35]
	s_lshl_b32 s16, s48, 2
	v_lshl_add_u64 v[34:35], v[34:35], 0, s[16:17]
	global_store_dword v[34:35], v36, off
; __device__ __forceinline__ unsigned cvtpk(float lo, float hi) { f32x2 v = {lo, hi}; bf16x2_t b = __builtin_convertvector(v, bf16x2_t); return __builtin_bit_cast(unsigned, b); }
; template <int X> __device__ __forceinline__ float xorl(float v) { return __int_as_float(__builtin_amdgcn_ds_swizzle(__float_as_int(v), (X << 10) | 0x1f)); }
; __device__ __forceinline__ float sum32(float v) { auto rr = __builtin_amdgcn_permlane32_swap(__float_as_uint(v), __float_as_uint(v), false, false); return __uint_as_float(rr[0]) + __uint_as_float(rr[1]); }
;     __device__ __forceinline__ void operator()(const f32x4 (&acc)[2][2][4][2], const Unit& u, int ui, int wr, int wc, int fr, int fq) const {
;     ...
;             for (int m = 0; m < 4; ++m) { const int row = u.pm * 256 + ai * HALF + wr * 64 + m * 16 + fr; bf16_t* rp = xb + (size_t)row * D + col0; float ss = 0.f;
; #pragma unroll
;                 for (int bj = 0; bj < 2; ++bj) { f32x4 b0, b1; const u32x4 rw = raw[m][bj];
;                     b0[0] = __uint_as_float(rw.x << 16); b0[1] = __uint_as_float(rw.x & 0xffff0000u); b0[2] = __uint_as_float(rw.y << 16); b0[3] = __uint_as_float(rw.y & 0xffff0000u);
;                     b1[0] = __uint_as_float(rw.z << 16); b1[1] = __uint_as_float(rw.z & 0xffff0000u); b1[2] = __uint_as_float(rw.w << 16); b1[3] = __uint_as_float(rw.w & 0xffff0000u);
;                     const f32x4 o0 = b0 + acc[ai][bj][m][0] * cs[bj][0], o1 = b1 + acc[ai][bj][m][1] * cs[bj][1];
;                     ss += ((o0[0] * o0[0] + o0[1] * o0[1]) + (o0[2] * o0[2] + o0[3] * o0[3])) + ((o1[0] * o1[0] + o1[1] * o1[1]) + (o1[2] * o1[2] + o1[3] * o1[3]));
;                     u32x4 w; w.x = cvtpk(o0[0], o0[1]); w.y = cvtpk(o0[2], o0[3]); w.z = cvtpk(o1[0], o1[1]); w.w = cvtpk(o1[2], o1[3]); *(u32x4*)(rp + bj * HALF) = w; }
;                 ss += xorl<16>(ss); ss = sum32(ss);
;                 if (fq == 0) ssq[(size_t)row * 16 + u.pn * 4 + wc] = ss; }
.LBB0_1252:
	s_or_b64 exec, exec, s[28:29]
	v_lshlrev_b32_e32 v36, 16, v78
	v_and_b32_e32 v37, 0xffff0000, v78
	v_lshlrev_b32_e32 v38, 16, v79
	v_and_b32_e32 v39, 0xffff0000, v79
	v_lshlrev_b32_e32 v40, 16, v80
	v_and_b32_e32 v41, 0xffff0000, v80
	v_lshlrev_b32_e32 v42, 16, v81
	v_and_b32_e32 v43, 0xffff0000, v81
	v_pk_add_f32 v[32:33], v[32:33], v[38:39]
	v_pk_add_f32 v[30:31], v[30:31], v[36:37]
	v_pk_add_f32 v[36:37], v[28:29], v[42:43]
	v_pk_add_f32 v[28:29], v[26:27], v[40:41]
	v_mul_f32_e32 v26, v31, v31
	v_mul_f32_e32 v27, v33, v33
	v_fmac_f32_e32 v26, v30, v30
	v_fmac_f32_e32 v27, v32, v32
	v_add_f32_e32 v26, v26, v27
	v_mul_f32_e32 v27, v29, v29
	v_mul_f32_e32 v38, v37, v37
	v_lshlrev_b64 v[34:35], 11, v[92:93]
	v_fmac_f32_e32 v27, v28, v28
	v_fmac_f32_e32 v38, v36, v36
	v_lshl_add_u64 v[34:35], s[8:9], 0, v[34:35]
	v_add_f32_e32 v27, v27, v38
	v_lshl_add_u64 v[34:35], v[164:165], 1, v[34:35]
	v_add_f32_e32 v38, v26, v27
	v_cvt_pk_bf16_f32 v26, v30, v31
	v_cvt_pk_bf16_f32 v27, v32, v33
	v_cvt_pk_bf16_f32 v28, v28, v29
	v_cvt_pk_bf16_f32 v29, v36, v37
	global_store_dwordx4 v[34:35], v[26:29], off
	v_lshlrev_b32_e32 v30, 16, v76
	v_and_b32_e32 v31, 0xffff0000, v76
	v_lshlrev_b32_e32 v26, 16, v74
	v_and_b32_e32 v27, 0xffff0000, v74
	v_lshlrev_b32_e32 v28, 16, v75
	v_and_b32_e32 v29, 0xffff0000, v75
	v_lshlrev_b32_e32 v32, 16, v77
	v_and_b32_e32 v33, 0xffff0000, v77
	v_pk_add_f32 v[24:25], v[24:25], v[28:29]
	v_pk_add_f32 v[22:23], v[22:23], v[26:27]
	v_pk_add_f32 v[26:27], v[20:21], v[32:33]
	v_pk_add_f32 v[20:21], v[18:19], v[30:31]
	v_mul_f32_e32 v18, v23, v23
	v_mul_f32_e32 v19, v25, v25
	v_fmac_f32_e32 v18, v22, v22
	v_fmac_f32_e32 v19, v24, v24
	v_add_f32_e32 v18, v18, v19
	v_mul_f32_e32 v19, v21, v21
	v_mul_f32_e32 v28, v27, v27
	v_fmac_f32_e32 v19, v20, v20
	v_fmac_f32_e32 v28, v26, v26
	v_add_f32_e32 v19, v19, v28
	v_add_f32_e32 v18, v18, v19
	v_add_f32_e32 v28, v38, v18
	v_cvt_pk_bf16_f32 v18, v22, v23
	ds_swizzle_b32 v22, v28 offset:swizzle(SWAP,16)
	v_cvt_pk_bf16_f32 v19, v24, v25
	v_cvt_pk_bf16_f32 v20, v20, v21
	v_cvt_pk_bf16_f32 v21, v26, v27
	global_store_dwordx4 v[34:35], v[18:21], off offset:256
	s_waitcnt lgkmcnt(0)
	s_nop 0
	v_add_f32_e32 v18, v28, v22
	v_mov_b32_e32 v19, v18
	s_nop 1
	v_permlane32_swap_b32_e32 v18, v19
	s_and_saveexec_b64 s[28:29], vcc
	s_cbranch_execz .LBB0_1254
	v_add_f32_e32 v20, v18, v19
	s_lshl_b32 s30, s43, 2
	v_lshlrev_b64 v[18:19], 6, v[92:93]
	s_ashr_i32 s31, s30, 31
	v_lshl_add_u64 v[18:19], s[10:11], 0, v[18:19]
	v_lshl_add_u64 v[18:19], s[30:31], 2, v[18:19]
	s_lshl_b32 s16, s48, 2
	v_lshl_add_u64 v[18:19], v[18:19], 0, s[16:17]
	global_store_dword v[18:19], v20, off
.LBB0_1254:
	s_or_b64 exec, exec, s[28:29]
	v_lshlrev_b32_e32 v20, 16, v70
	v_and_b32_e32 v21, 0xffff0000, v70
	v_lshlrev_b32_e32 v22, 16, v71
	v_and_b32_e32 v23, 0xffff0000, v71
	v_lshlrev_b32_e32 v24, 16, v72
	v_and_b32_e32 v25, 0xffff0000, v72
	v_lshlrev_b32_e32 v26, 16, v73
	v_and_b32_e32 v27, 0xffff0000, v73
	v_pk_add_f32 v[16:17], v[16:17], v[22:23]
	v_pk_add_f32 v[14:15], v[14:15], v[20:21]
	v_pk_add_f32 v[20:21], v[12:13], v[26:27]
	v_pk_add_f32 v[12:13], v[10:11], v[24:25]
	v_mul_f32_e32 v10, v15, v15
	v_mul_f32_e32 v11, v17, v17
	v_fmac_f32_e32 v10, v14, v14
	v_fmac_f32_e32 v11, v16, v16
	v_add_f32_e32 v10, v10, v11
	v_mul_f32_e32 v11, v13, v13
	v_mul_f32_e32 v22, v21, v21
	v_lshlrev_b64 v[18:19], 11, v[90:91]
	v_fmac_f32_e32 v11, v12, v12
	v_fmac_f32_e32 v22, v20, v20
	v_lshl_add_u64 v[18:19], s[8:9], 0, v[18:19]
	v_add_f32_e32 v11, v11, v22
	v_lshl_add_u64 v[18:19], v[164:165], 1, v[18:19]
	v_add_f32_e32 v22, v10, v11
	v_cvt_pk_bf16_f32 v10, v14, v15
	v_cvt_pk_bf16_f32 v11, v16, v17
	v_cvt_pk_bf16_f32 v12, v12, v13
	v_cvt_pk_bf16_f32 v13, v20, v21
	global_store_dwordx4 v[18:19], v[10:13], off
	v_lshlrev_b32_e32 v14, 16, v68
	v_and_b32_e32 v15, 0xffff0000, v68
	v_lshlrev_b32_e32 v10, 16, v66
	v_and_b32_e32 v11, 0xffff0000, v66
	v_lshlrev_b32_e32 v12, 16, v67
	v_and_b32_e32 v13, 0xffff0000, v67
	v_lshlrev_b32_e32 v16, 16, v69
	v_and_b32_e32 v17, 0xffff0000, v69
	v_pk_add_f32 v[8:9], v[8:9], v[12:13]
	v_pk_add_f32 v[6:7], v[6:7], v[10:11]
	v_pk_add_f32 v[10:11], v[4:5], v[16:17]
	v_pk_add_f32 v[4:5], v[2:3], v[14:15]
	v_mul_f32_e32 v2, v7, v7
	v_mul_f32_e32 v3, v9, v9
	v_fmac_f32_e32 v2, v6, v6
	v_fmac_f32_e32 v3, v8, v8
	v_add_f32_e32 v2, v2, v3
	v_mul_f32_e32 v3, v5, v5
	v_mul_f32_e32 v12, v11, v11
	v_fmac_f32_e32 v3, v4, v4
	v_fmac_f32_e32 v12, v10, v10
	v_add_f32_e32 v3, v3, v12
	v_add_f32_e32 v2, v2, v3
	v_add_f32_e32 v12, v22, v2
	v_cvt_pk_bf16_f32 v2, v6, v7
	ds_swizzle_b32 v6, v12 offset:swizzle(SWAP,16)
	v_cvt_pk_bf16_f32 v3, v8, v9
	v_cvt_pk_bf16_f32 v4, v4, v5
	v_cvt_pk_bf16_f32 v5, v10, v11
	global_store_dwordx4 v[18:19], v[2:5], off offset:256
	s_waitcnt lgkmcnt(0)
	s_nop 0
	v_add_f32_e32 v2, v12, v6
	v_mov_b32_e32 v3, v2
	s_nop 1
	v_permlane32_swap_b32_e32 v2, v3
	s_and_saveexec_b64 s[28:29], vcc
	s_cbranch_execz .LBB0_1256
	v_add_f32_e32 v4, v2, v3
	s_lshl_b32 s30, s43, 2
	v_lshlrev_b64 v[2:3], 6, v[90:91]
	s_ashr_i32 s31, s30, 31
	v_lshl_add_u64 v[2:3], s[10:11], 0, v[2:3]
	v_lshl_add_u64 v[2:3], s[30:31], 2, v[2:3]
	s_lshl_b32 s16, s48, 2
	v_lshl_add_u64 v[2:3], v[2:3], 0, s[16:17]
	global_store_dword v[2:3], v4, off
